# v46 plus GEMM unit-order math constant-folded (group size is always 8 for M=32768): drops a v_rcp/readfirstlane division chain per unit
# baseline (speedup 1.0000x reference)
.LBB0_135:
	s_add_i32 s58, s58, 1
	s_mul_i32 s2, s58, s51
	s_mul_hi_u32 s3, s58, s16
	s_add_i32 s3, s3, s2
	s_mul_i32 s2, s58, s16
	v_readlane_b32 s4, v255, 16
	s_add_u32 s2, s2, s4
	s_addc_u32 s3, s3, s7
	v_mov_b64_e32 v[2:3], 0x700
	v_cmp_lt_i64_e64 s[38:39], s[2:3], v[2:3]
	v_mov_b64_e32 v[2:3], 0x6ff
	v_cmp_gt_i64_e32 vcc, s[2:3], v[2:3]
	s_cbranch_vccnz .LBB0_137
	s_ashr_i32 s3, s2, 31
	s_lshr_b32 s3, s3, 29
	s_add_i32 s3, s2, s3
	s_ashr_i32 s4, s3, 3
	s_and_b32 s3, s3, -8
	s_sub_i32 s2, s2, s3
	s_cmp_lt_i32 s2, 0
	s_movk_i32 s3, 0xe1
	s_cselect_b32 s3, s3, 0xe0
	s_mul_i32 s2, s2, s3
	s_add_i32 s2, s2, s4
	s_mul_hi_i32 s3, s2, 0x92492493
	s_add_i32 s3, s3, s2
	s_lshr_b32 s4, s3, 31
	s_ashr_i32 s3, s3, 6
	s_add_i32 s3, s3, s4
	s_lshl_b32 s4, s3, 3
	s_sub_i32 s5, 0x80, s4
	s_min_i32 s5, s5, 8
	s_mulk_i32 s3, 0x70
	s_sub_i32 s2, s2, s3
	s_lshr_b32 s42, s2, 3
	s_and_b32 s2, s2, 7
	s_add_i32 s44, s4, s2

.LBB0_378:
	s_ashr_i32 s2, s20, 3
	s_add_i32 s2, s40, s2
	s_ashr_i32 s3, s2, 31
	s_lshr_b32 s3, s3, 27
	s_add_i32 s3, s2, s3
	s_ashr_i32 s20, s3, 5
	s_lshl_b32 s20, s20, 3
	s_sub_i32 s21, 0x80, s20
	s_min_i32 s21, s21, 8
	s_andn2_b32 s3, s3, 31
	s_sub_i32 s2, s2, s3
	s_lshr_b32 s65, s2, 3
	s_and_b32 s2, s2, 7
	s_add_i32 s66, s20, s2

.LBB0_558:
	s_add_i32 s56, s56, 1
	s_mul_i32 s2, s56, s53
	s_mul_hi_u32 s3, s56, s16
	s_add_i32 s3, s3, s2
	s_mul_i32 s2, s56, s16
	s_add_u32 s2, s2, s66
	s_addc_u32 s3, s3, s49
	v_mov_b64_e32 v[2:3], 0xb00
	v_cmp_lt_i64_e64 s[38:39], s[2:3], v[2:3]
	v_mov_b64_e32 v[2:3], 0xaff
	v_cmp_gt_i64_e32 vcc, s[2:3], v[2:3]
	s_cbranch_vccnz .LBB0_560
	s_ashr_i32 s3, s2, 31
	s_lshr_b32 s3, s3, 29
	s_add_i32 s3, s2, s3
	s_ashr_i32 s6, s3, 3
	s_and_b32 s3, s3, -8
	s_sub_i32 s2, s2, s3
	s_cmp_lt_i32 s2, 0
	s_movk_i32 s3, 0x161
	s_cselect_b32 s3, s3, 0x160
	s_mul_i32 s2, s2, s3
	s_add_i32 s2, s2, s6
	s_mul_hi_i32 s3, s2, 0x2e8ba2e9
	s_lshr_b32 s6, s3, 31
	s_ashr_i32 s3, s3, 5
	s_add_i32 s3, s3, s6
	s_lshl_b32 s6, s3, 3
	s_sub_i32 s7, 0x80, s6
	s_min_i32 s7, s7, 8
	s_mulk_i32 s3, 0xb0
	s_sub_i32 s2, s2, s3
	s_lshr_b32 s34, s2, 3
	s_and_b32 s2, s2, 7
	s_add_i32 s36, s6, s2
